# selected-branch loop: lazy reference move only when a tile row sum exceeds 2^24 (was 2^8)
# baseline (speedup 1.0000x reference)
.Lsel_nodiag_0b:
	v_add_u32_e32 v187, s81, v208
	ds_read_b128 v[124:127], v187 offset:9216
	ds_read_b128 v[144:147], v187 offset:13824
	ds_read_b128 v[148:151], v187 offset:9248
	v_exp_f32_e32 v80, v80
	v_exp_f32_e32 v81, v81
	v_exp_f32_e32 v82, v82
	v_exp_f32_e32 v83, v83
	s_waitcnt lgkmcnt(6)
	v_mfma_f32_32x32x16_bf16 v[238:253], v[108:111], v[128:131], v[2:17]
	ds_read_b128 v[108:111], v0 offset:64
	v_exp_f32_e32 v84, v84
	v_exp_f32_e32 v85, v85
	v_exp_f32_e32 v86, v86
	v_exp_f32_e32 v87, v87
	s_waitcnt lgkmcnt(6)
	v_mfma_f32_32x32x16_bf16 v[222:237], v[112:115], v[128:131], v[2:17]
	ds_read_b128 v[112:115], v0 offset:4672
	v_add_f32_e32 v164, 0, v80
	v_add_f32_e32 v165, 0, v81
	v_add_f32_e32 v164, v82, v164
	v_add_f32_e32 v165, v83, v165
	v_cvt_pk_bf16_f32 v80, v80, v81
	v_cvt_pk_bf16_f32 v81, v82, v83
	v_add_f32_e32 v164, v84, v164
	v_add_f32_e32 v165, v85, v165
	v_add_f32_e32 v164, v86, v164
	v_add_f32_e32 v165, v87, v165
	v_cvt_pk_bf16_f32 v82, v84, v85
	v_cvt_pk_bf16_f32 v83, v86, v87
	v_cndmask_b32_e64 v80, v80, 0, s[72:73]
	v_cndmask_b32_e64 v81, v81, 0, s[72:73]
	v_cndmask_b32_e64 v82, v82, 0, s[72:73]
	v_cndmask_b32_e64 v83, v83, 0, s[72:73]
	v_exp_f32_e32 v88, v88
	v_exp_f32_e32 v89, v89
	s_waitcnt lgkmcnt(4)
	v_mfma_f32_32x32x16_bf16 v[48:63], v[124:127], v[80:83], v[48:63]
	ds_read_b128 v[124:127], v187 offset:13856
	v_exp_f32_e32 v90, v90
	v_exp_f32_e32 v91, v91
	s_waitcnt lgkmcnt(4)
	v_mfma_f32_32x32x16_bf16 v[32:47], v[144:147], v[80:83], v[32:47]
	ds_read_b128 v[144:147], v187 offset:9280
	v_exp_f32_e32 v92, v92
	v_exp_f32_e32 v93, v93
	v_mfma_f32_32x32x16_bf16 v[238:253], v[116:119], v[132:135], v[238:253]
	ds_read_b128 v[116:119], v0 offset:96
	v_exp_f32_e32 v94, v94
	v_exp_f32_e32 v95, v95
	v_mfma_f32_32x32x16_bf16 v[222:237], v[120:123], v[132:135], v[222:237]
	ds_read_b128 v[120:123], v0 offset:4704
	v_add_f32_e32 v164, v88, v164
	v_add_f32_e32 v165, v89, v165
	v_add_f32_e32 v164, v90, v164
	v_add_f32_e32 v165, v91, v165
	v_cvt_pk_bf16_f32 v88, v88, v89
	v_cvt_pk_bf16_f32 v89, v90, v91
	v_add_f32_e32 v164, v92, v164
	v_add_f32_e32 v165, v93, v165
	v_add_f32_e32 v164, v94, v164
	v_add_f32_e32 v165, v95, v165
	v_cvt_pk_bf16_f32 v90, v92, v93
	v_cvt_pk_bf16_f32 v91, v94, v95
	v_cndmask_b32_e64 v88, v88, 0, s[72:73]
	v_cndmask_b32_e64 v89, v89, 0, s[72:73]
	v_cndmask_b32_e64 v90, v90, 0, s[72:73]
	v_cndmask_b32_e64 v91, v91, 0, s[72:73]
	v_exp_f32_e32 v64, v64
	v_exp_f32_e32 v65, v65
	s_waitcnt lgkmcnt(6)
	v_mfma_f32_32x32x16_bf16 v[48:63], v[148:151], v[88:91], v[48:63]
	ds_read_b128 v[148:151], v187 offset:13888
	v_exp_f32_e32 v66, v66
	v_exp_f32_e32 v67, v67
	s_waitcnt lgkmcnt(4)
	v_mfma_f32_32x32x16_bf16 v[32:47], v[124:127], v[88:91], v[32:47]
	ds_read_b128 v[124:127], v187 offset:9312
	v_exp_f32_e32 v68, v68
	v_exp_f32_e32 v69, v69
	v_mfma_f32_32x32x16_bf16 v[238:253], v[108:111], v[136:139], v[238:253]
	v_exp_f32_e32 v70, v70
	v_exp_f32_e32 v71, v71
	v_mfma_f32_32x32x16_bf16 v[222:237], v[112:115], v[136:139], v[222:237]
	v_add_f32_e32 v164, v64, v164
	v_add_f32_e32 v165, v65, v165
	v_add_f32_e32 v164, v66, v164
	v_add_f32_e32 v165, v67, v165
	v_cvt_pk_bf16_f32 v64, v64, v65
	v_cvt_pk_bf16_f32 v65, v66, v67
	v_add_f32_e32 v164, v68, v164
	v_add_f32_e32 v165, v69, v165
	v_add_f32_e32 v164, v70, v164
	v_add_f32_e32 v165, v71, v165
	v_cvt_pk_bf16_f32 v66, v68, v69
	v_cvt_pk_bf16_f32 v67, v70, v71
	v_cndmask_b32_e64 v64, v64, 0, s[72:73]
	v_cndmask_b32_e64 v65, v65, 0, s[72:73]
	v_cndmask_b32_e64 v66, v66, 0, s[72:73]
	v_cndmask_b32_e64 v67, v67, 0, s[72:73]
	v_exp_f32_e32 v72, v72
	v_exp_f32_e32 v73, v73
	s_waitcnt lgkmcnt(4)
	v_mfma_f32_32x32x16_bf16 v[48:63], v[144:147], v[64:67], v[48:63]
	ds_read_b128 v[144:147], v187 offset:13920
	v_exp_f32_e32 v74, v74
	v_exp_f32_e32 v75, v75
	s_waitcnt lgkmcnt(2)
	v_mfma_f32_32x32x16_bf16 v[32:47], v[148:151], v[64:67], v[32:47]
	v_exp_f32_e32 v76, v76
	v_exp_f32_e32 v77, v77
	v_mfma_f32_32x32x16_bf16 v[238:253], v[116:119], v[140:143], v[238:253]
	v_exp_f32_e32 v78, v78
	v_exp_f32_e32 v79, v79
	v_mfma_f32_32x32x16_bf16 v[222:237], v[120:123], v[140:143], v[222:237]
	v_add_f32_e32 v164, v72, v164
	v_add_f32_e32 v165, v73, v165
	v_add_f32_e32 v164, v74, v164
	v_add_f32_e32 v165, v75, v165
	v_cvt_pk_bf16_f32 v72, v72, v73
	v_cvt_pk_bf16_f32 v73, v74, v75
	v_add_f32_e32 v164, v76, v164
	v_add_f32_e32 v165, v77, v165
	v_add_f32_e32 v164, v78, v164
	v_add_f32_e32 v165, v79, v165
	v_cvt_pk_bf16_f32 v74, v76, v77
	v_cvt_pk_bf16_f32 v75, v78, v79
	v_cndmask_b32_e64 v72, v72, 0, s[72:73]
	v_cndmask_b32_e64 v73, v73, 0, s[72:73]
	v_cndmask_b32_e64 v74, v74, 0, s[72:73]
	v_cndmask_b32_e64 v75, v75, 0, s[72:73]
	s_nop 1
	s_waitcnt lgkmcnt(1)
	v_mfma_f32_32x32x16_bf16 v[48:63], v[124:127], v[72:75], v[48:63]
	s_waitcnt lgkmcnt(0)
	v_mfma_f32_32x32x16_bf16 v[32:47], v[144:147], v[72:75], v[32:47]
	v_add_f32_e32 v164, v164, v165
	v_cndmask_b32_e64 v164, v164, 0, s[72:73]
	v_add_f32_e32 v106, v106, v164
	v_cmp_lt_f32_e32 vcc, 0x4b800000, v164
	s_cbranch_vccz .Lsel_noresc_0b
	s_nop 15
	s_nop 15
	v_mov_b32_e32 v107, v164
	s_nop 1
	v_permlane32_swap_b32_e32 v164, v107
	v_add_f32_e32 v164, v164, v107
	v_log_f32_e32 v160, v164
	s_nop 0
	v_max_f32_e32 v160, 0, v160
	v_exp_f32_e64 v162, -v160
	v_sub_f32_e32 v2, v2, v160
	v_sub_f32_e32 v3, v3, v160
	v_sub_f32_e32 v4, v4, v160
	v_sub_f32_e32 v5, v5, v160
	v_sub_f32_e32 v6, v6, v160
	v_sub_f32_e32 v7, v7, v160
	v_sub_f32_e32 v8, v8, v160
	v_sub_f32_e32 v9, v9, v160
	v_sub_f32_e32 v10, v10, v160
	v_sub_f32_e32 v11, v11, v160
	v_sub_f32_e32 v12, v12, v160
	v_sub_f32_e32 v13, v13, v160
	v_sub_f32_e32 v14, v14, v160
	v_sub_f32_e32 v15, v15, v160
	v_sub_f32_e32 v16, v16, v160
	v_sub_f32_e32 v17, v17, v160
	v_mul_f32_e32 v106, v106, v162
	v_pk_mul_f32 v[48:49], v[48:49], v[162:163] op_sel_hi:[1,0]
	v_pk_mul_f32 v[32:33], v[32:33], v[162:163] op_sel_hi:[1,0]
	v_pk_mul_f32 v[50:51], v[50:51], v[162:163] op_sel_hi:[1,0]
	v_pk_mul_f32 v[34:35], v[34:35], v[162:163] op_sel_hi:[1,0]
	v_pk_mul_f32 v[52:53], v[52:53], v[162:163] op_sel_hi:[1,0]
	v_pk_mul_f32 v[36:37], v[36:37], v[162:163] op_sel_hi:[1,0]
	v_pk_mul_f32 v[54:55], v[54:55], v[162:163] op_sel_hi:[1,0]
	v_pk_mul_f32 v[38:39], v[38:39], v[162:163] op_sel_hi:[1,0]
	v_pk_mul_f32 v[56:57], v[56:57], v[162:163] op_sel_hi:[1,0]
	v_pk_mul_f32 v[40:41], v[40:41], v[162:163] op_sel_hi:[1,0]
	v_pk_mul_f32 v[58:59], v[58:59], v[162:163] op_sel_hi:[1,0]
	v_pk_mul_f32 v[42:43], v[42:43], v[162:163] op_sel_hi:[1,0]
	v_pk_mul_f32 v[60:61], v[60:61], v[162:163] op_sel_hi:[1,0]
	v_pk_mul_f32 v[44:45], v[44:45], v[162:163] op_sel_hi:[1,0]
	v_pk_mul_f32 v[62:63], v[62:63], v[162:163] op_sel_hi:[1,0]
	v_pk_mul_f32 v[46:47], v[46:47], v[162:163] op_sel_hi:[1,0]
	v_pk_add_f32 v[238:239], v[238:239], v[160:161] op_sel_hi:[1,0] neg_lo:[0,1] neg_hi:[0,1]
	v_pk_add_f32 v[222:223], v[222:223], v[160:161] op_sel_hi:[1,0] neg_lo:[0,1] neg_hi:[0,1]
	v_pk_add_f32 v[240:241], v[240:241], v[160:161] op_sel_hi:[1,0] neg_lo:[0,1] neg_hi:[0,1]
	v_pk_add_f32 v[224:225], v[224:225], v[160:161] op_sel_hi:[1,0] neg_lo:[0,1] neg_hi:[0,1]
	v_pk_add_f32 v[242:243], v[242:243], v[160:161] op_sel_hi:[1,0] neg_lo:[0,1] neg_hi:[0,1]
	v_pk_add_f32 v[226:227], v[226:227], v[160:161] op_sel_hi:[1,0] neg_lo:[0,1] neg_hi:[0,1]
	v_pk_add_f32 v[244:245], v[244:245], v[160:161] op_sel_hi:[1,0] neg_lo:[0,1] neg_hi:[0,1]
	v_pk_add_f32 v[228:229], v[228:229], v[160:161] op_sel_hi:[1,0] neg_lo:[0,1] neg_hi:[0,1]
	v_pk_add_f32 v[246:247], v[246:247], v[160:161] op_sel_hi:[1,0] neg_lo:[0,1] neg_hi:[0,1]
	v_pk_add_f32 v[230:231], v[230:231], v[160:161] op_sel_hi:[1,0] neg_lo:[0,1] neg_hi:[0,1]
	v_pk_add_f32 v[248:249], v[248:249], v[160:161] op_sel_hi:[1,0] neg_lo:[0,1] neg_hi:[0,1]
	v_pk_add_f32 v[232:233], v[232:233], v[160:161] op_sel_hi:[1,0] neg_lo:[0,1] neg_hi:[0,1]
	v_pk_add_f32 v[250:251], v[250:251], v[160:161] op_sel_hi:[1,0] neg_lo:[0,1] neg_hi:[0,1]
	v_pk_add_f32 v[234:235], v[234:235], v[160:161] op_sel_hi:[1,0] neg_lo:[0,1] neg_hi:[0,1]
	v_pk_add_f32 v[252:253], v[252:253], v[160:161] op_sel_hi:[1,0] neg_lo:[0,1] neg_hi:[0,1]
	v_pk_add_f32 v[236:237], v[236:237], v[160:161] op_sel_hi:[1,0] neg_lo:[0,1] neg_hi:[0,1]
	s_nop 1

.Lsel_nodiag_0c:
	v_add_u32_e32 v187, s81, v208
	ds_read_b128 v[124:127], v187 offset:9216
	ds_read_b128 v[144:147], v187 offset:13824
	ds_read_b128 v[148:151], v187 offset:9248
	v_exp_f32_e32 v80, v80
	v_exp_f32_e32 v81, v81
	v_exp_f32_e32 v82, v82
	v_exp_f32_e32 v83, v83
	v_exp_f32_e32 v84, v84
	v_exp_f32_e32 v85, v85
	v_exp_f32_e32 v86, v86
	v_exp_f32_e32 v87, v87
	v_add_f32_e32 v164, 0, v80
	v_add_f32_e32 v165, 0, v81
	v_add_f32_e32 v164, v82, v164
	v_add_f32_e32 v165, v83, v165
	v_cvt_pk_bf16_f32 v80, v80, v81
	v_cvt_pk_bf16_f32 v81, v82, v83
	v_add_f32_e32 v164, v84, v164
	v_add_f32_e32 v165, v85, v165
	v_add_f32_e32 v164, v86, v164
	v_add_f32_e32 v165, v87, v165
	v_cvt_pk_bf16_f32 v82, v84, v85
	v_cvt_pk_bf16_f32 v83, v86, v87
	v_cndmask_b32_e64 v80, v80, 0, s[72:73]
	v_cndmask_b32_e64 v81, v81, 0, s[72:73]
	v_cndmask_b32_e64 v82, v82, 0, s[72:73]
	v_cndmask_b32_e64 v83, v83, 0, s[72:73]
	v_exp_f32_e32 v88, v88
	v_exp_f32_e32 v89, v89
	s_waitcnt lgkmcnt(2)
	v_mfma_f32_32x32x16_bf16 v[48:63], v[124:127], v[80:83], v[48:63]
	ds_read_b128 v[124:127], v187 offset:13856
	v_exp_f32_e32 v90, v90
	v_exp_f32_e32 v91, v91
	s_waitcnt lgkmcnt(2)
	v_mfma_f32_32x32x16_bf16 v[32:47], v[144:147], v[80:83], v[32:47]
	ds_read_b128 v[144:147], v187 offset:9280
	v_exp_f32_e32 v92, v92
	v_exp_f32_e32 v93, v93
	v_exp_f32_e32 v94, v94
	v_exp_f32_e32 v95, v95
	v_add_f32_e32 v164, v88, v164
	v_add_f32_e32 v165, v89, v165
	v_add_f32_e32 v164, v90, v164
	v_add_f32_e32 v165, v91, v165
	v_cvt_pk_bf16_f32 v88, v88, v89
	v_cvt_pk_bf16_f32 v89, v90, v91
	v_add_f32_e32 v164, v92, v164
	v_add_f32_e32 v165, v93, v165
	v_add_f32_e32 v164, v94, v164
	v_add_f32_e32 v165, v95, v165
	v_cvt_pk_bf16_f32 v90, v92, v93
	v_cvt_pk_bf16_f32 v91, v94, v95
	v_cndmask_b32_e64 v88, v88, 0, s[72:73]
	v_cndmask_b32_e64 v89, v89, 0, s[72:73]
	v_cndmask_b32_e64 v90, v90, 0, s[72:73]
	v_cndmask_b32_e64 v91, v91, 0, s[72:73]
	v_exp_f32_e32 v64, v64
	v_exp_f32_e32 v65, v65
	s_waitcnt lgkmcnt(2)
	v_mfma_f32_32x32x16_bf16 v[48:63], v[148:151], v[88:91], v[48:63]
	ds_read_b128 v[148:151], v187 offset:13888
	v_exp_f32_e32 v66, v66
	v_exp_f32_e32 v67, v67
	s_waitcnt lgkmcnt(2)
	v_mfma_f32_32x32x16_bf16 v[32:47], v[124:127], v[88:91], v[32:47]
	ds_read_b128 v[124:127], v187 offset:9312
	v_exp_f32_e32 v68, v68
	v_exp_f32_e32 v69, v69
	v_exp_f32_e32 v70, v70
	v_exp_f32_e32 v71, v71
	v_add_f32_e32 v164, v64, v164
	v_add_f32_e32 v165, v65, v165
	v_add_f32_e32 v164, v66, v164
	v_add_f32_e32 v165, v67, v165
	v_cvt_pk_bf16_f32 v64, v64, v65
	v_cvt_pk_bf16_f32 v65, v66, v67
	v_add_f32_e32 v164, v68, v164
	v_add_f32_e32 v165, v69, v165
	v_add_f32_e32 v164, v70, v164
	v_add_f32_e32 v165, v71, v165
	v_cvt_pk_bf16_f32 v66, v68, v69
	v_cvt_pk_bf16_f32 v67, v70, v71
	v_cndmask_b32_e64 v64, v64, 0, s[72:73]
	v_cndmask_b32_e64 v65, v65, 0, s[72:73]
	v_cndmask_b32_e64 v66, v66, 0, s[72:73]
	v_cndmask_b32_e64 v67, v67, 0, s[72:73]
	v_exp_f32_e32 v72, v72
	v_exp_f32_e32 v73, v73
	s_waitcnt lgkmcnt(2)
	v_mfma_f32_32x32x16_bf16 v[48:63], v[144:147], v[64:67], v[48:63]
	ds_read_b128 v[144:147], v187 offset:13920
	v_exp_f32_e32 v74, v74
	v_exp_f32_e32 v75, v75
	s_waitcnt lgkmcnt(2)
	v_mfma_f32_32x32x16_bf16 v[32:47], v[148:151], v[64:67], v[32:47]
	v_exp_f32_e32 v76, v76
	v_exp_f32_e32 v77, v77
	v_exp_f32_e32 v78, v78
	v_exp_f32_e32 v79, v79
	v_add_f32_e32 v164, v72, v164
	v_add_f32_e32 v165, v73, v165
	v_add_f32_e32 v164, v74, v164
	v_add_f32_e32 v165, v75, v165
	v_cvt_pk_bf16_f32 v72, v72, v73
	v_cvt_pk_bf16_f32 v73, v74, v75
	v_add_f32_e32 v164, v76, v164
	v_add_f32_e32 v165, v77, v165
	v_add_f32_e32 v164, v78, v164
	v_add_f32_e32 v165, v79, v165
	v_cvt_pk_bf16_f32 v74, v76, v77
	v_cvt_pk_bf16_f32 v75, v78, v79
	v_cndmask_b32_e64 v72, v72, 0, s[72:73]
	v_cndmask_b32_e64 v73, v73, 0, s[72:73]
	v_cndmask_b32_e64 v74, v74, 0, s[72:73]
	v_cndmask_b32_e64 v75, v75, 0, s[72:73]
	s_nop 1
	s_waitcnt lgkmcnt(1)
	v_mfma_f32_32x32x16_bf16 v[48:63], v[124:127], v[72:75], v[48:63]
	s_waitcnt lgkmcnt(0)
	v_mfma_f32_32x32x16_bf16 v[32:47], v[144:147], v[72:75], v[32:47]
	v_add_f32_e32 v164, v164, v165
	v_cndmask_b32_e64 v164, v164, 0, s[72:73]
	v_add_f32_e32 v106, v106, v164
	v_cmp_lt_f32_e32 vcc, 0x4b800000, v164
	s_cbranch_vccz .Lsel_noresc_0c
	s_nop 15
	s_nop 15
	v_mov_b32_e32 v107, v164
	s_nop 1
	v_permlane32_swap_b32_e32 v164, v107
	v_add_f32_e32 v164, v164, v107
	v_log_f32_e32 v160, v164
	s_nop 0
	v_max_f32_e32 v160, 0, v160
	v_exp_f32_e64 v162, -v160
	v_sub_f32_e32 v2, v2, v160
	v_sub_f32_e32 v3, v3, v160
	v_sub_f32_e32 v4, v4, v160
	v_sub_f32_e32 v5, v5, v160
	v_sub_f32_e32 v6, v6, v160
	v_sub_f32_e32 v7, v7, v160
	v_sub_f32_e32 v8, v8, v160
	v_sub_f32_e32 v9, v9, v160
	v_sub_f32_e32 v10, v10, v160
	v_sub_f32_e32 v11, v11, v160
	v_sub_f32_e32 v12, v12, v160
	v_sub_f32_e32 v13, v13, v160
	v_sub_f32_e32 v14, v14, v160
	v_sub_f32_e32 v15, v15, v160
	v_sub_f32_e32 v16, v16, v160
	v_sub_f32_e32 v17, v17, v160
	v_mul_f32_e32 v106, v106, v162
	v_pk_mul_f32 v[48:49], v[48:49], v[162:163] op_sel_hi:[1,0]
	v_pk_mul_f32 v[32:33], v[32:33], v[162:163] op_sel_hi:[1,0]
	v_pk_mul_f32 v[50:51], v[50:51], v[162:163] op_sel_hi:[1,0]
	v_pk_mul_f32 v[34:35], v[34:35], v[162:163] op_sel_hi:[1,0]
	v_pk_mul_f32 v[52:53], v[52:53], v[162:163] op_sel_hi:[1,0]
	v_pk_mul_f32 v[36:37], v[36:37], v[162:163] op_sel_hi:[1,0]
	v_pk_mul_f32 v[54:55], v[54:55], v[162:163] op_sel_hi:[1,0]
	v_pk_mul_f32 v[38:39], v[38:39], v[162:163] op_sel_hi:[1,0]
	v_pk_mul_f32 v[56:57], v[56:57], v[162:163] op_sel_hi:[1,0]
	v_pk_mul_f32 v[40:41], v[40:41], v[162:163] op_sel_hi:[1,0]
	v_pk_mul_f32 v[58:59], v[58:59], v[162:163] op_sel_hi:[1,0]
	v_pk_mul_f32 v[42:43], v[42:43], v[162:163] op_sel_hi:[1,0]
	v_pk_mul_f32 v[60:61], v[60:61], v[162:163] op_sel_hi:[1,0]
	v_pk_mul_f32 v[44:45], v[44:45], v[162:163] op_sel_hi:[1,0]
	v_pk_mul_f32 v[62:63], v[62:63], v[162:163] op_sel_hi:[1,0]
	v_pk_mul_f32 v[46:47], v[46:47], v[162:163] op_sel_hi:[1,0]
	s_nop 1

.Lsel_nodiag_1b:
	v_add_u32_e32 v187, s81, v208
	ds_read_b128 v[124:127], v187 offset:9216
	ds_read_b128 v[144:147], v187 offset:13824
	ds_read_b128 v[148:151], v187 offset:9248
	v_exp_f32_e32 v238, v238
	v_exp_f32_e32 v239, v239
	v_exp_f32_e32 v240, v240
	v_exp_f32_e32 v241, v241
	s_waitcnt lgkmcnt(6)
	v_mfma_f32_32x32x16_bf16 v[80:95], v[108:111], v[128:131], v[2:17]
	ds_read_b128 v[108:111], v0 offset:64
	v_exp_f32_e32 v242, v242
	v_exp_f32_e32 v243, v243
	v_exp_f32_e32 v244, v244
	v_exp_f32_e32 v245, v245
	s_waitcnt lgkmcnt(6)
	v_mfma_f32_32x32x16_bf16 v[64:79], v[112:115], v[128:131], v[2:17]
	ds_read_b128 v[112:115], v0 offset:4672
	v_add_f32_e32 v164, 0, v238
	v_add_f32_e32 v165, 0, v239
	v_add_f32_e32 v164, v240, v164
	v_add_f32_e32 v165, v241, v165
	v_cvt_pk_bf16_f32 v238, v238, v239
	v_cvt_pk_bf16_f32 v239, v240, v241
	v_add_f32_e32 v164, v242, v164
	v_add_f32_e32 v165, v243, v165
	v_add_f32_e32 v164, v244, v164
	v_add_f32_e32 v165, v245, v165
	v_cvt_pk_bf16_f32 v240, v242, v243
	v_cvt_pk_bf16_f32 v241, v244, v245
	v_cndmask_b32_e64 v238, v238, 0, s[72:73]
	v_cndmask_b32_e64 v239, v239, 0, s[72:73]
	v_cndmask_b32_e64 v240, v240, 0, s[72:73]
	v_cndmask_b32_e64 v241, v241, 0, s[72:73]
	v_exp_f32_e32 v246, v246
	v_exp_f32_e32 v247, v247
	s_waitcnt lgkmcnt(4)
	v_mfma_f32_32x32x16_bf16 v[48:63], v[124:127], v[238:241], v[48:63]
	ds_read_b128 v[124:127], v187 offset:13856
	v_exp_f32_e32 v248, v248
	v_exp_f32_e32 v249, v249
	s_waitcnt lgkmcnt(4)
	v_mfma_f32_32x32x16_bf16 v[32:47], v[144:147], v[238:241], v[32:47]
	ds_read_b128 v[144:147], v187 offset:9280
	v_exp_f32_e32 v250, v250
	v_exp_f32_e32 v251, v251
	v_mfma_f32_32x32x16_bf16 v[80:95], v[116:119], v[132:135], v[80:95]
	ds_read_b128 v[116:119], v0 offset:96
	v_exp_f32_e32 v252, v252
	v_exp_f32_e32 v253, v253
	v_mfma_f32_32x32x16_bf16 v[64:79], v[120:123], v[132:135], v[64:79]
	ds_read_b128 v[120:123], v0 offset:4704
	v_add_f32_e32 v164, v246, v164
	v_add_f32_e32 v165, v247, v165
	v_add_f32_e32 v164, v248, v164
	v_add_f32_e32 v165, v249, v165
	v_cvt_pk_bf16_f32 v246, v246, v247
	v_cvt_pk_bf16_f32 v247, v248, v249
	v_add_f32_e32 v164, v250, v164
	v_add_f32_e32 v165, v251, v165
	v_add_f32_e32 v164, v252, v164
	v_add_f32_e32 v165, v253, v165
	v_cvt_pk_bf16_f32 v248, v250, v251
	v_cvt_pk_bf16_f32 v249, v252, v253
	v_cndmask_b32_e64 v246, v246, 0, s[72:73]
	v_cndmask_b32_e64 v247, v247, 0, s[72:73]
	v_cndmask_b32_e64 v248, v248, 0, s[72:73]
	v_cndmask_b32_e64 v249, v249, 0, s[72:73]
	v_exp_f32_e32 v222, v222
	v_exp_f32_e32 v223, v223
	s_waitcnt lgkmcnt(6)
	v_mfma_f32_32x32x16_bf16 v[48:63], v[148:151], v[246:249], v[48:63]
	ds_read_b128 v[148:151], v187 offset:13888
	v_exp_f32_e32 v224, v224
	v_exp_f32_e32 v225, v225
	s_waitcnt lgkmcnt(4)
	v_mfma_f32_32x32x16_bf16 v[32:47], v[124:127], v[246:249], v[32:47]
	ds_read_b128 v[124:127], v187 offset:9312
	v_exp_f32_e32 v226, v226
	v_exp_f32_e32 v227, v227
	v_mfma_f32_32x32x16_bf16 v[80:95], v[108:111], v[136:139], v[80:95]
	v_exp_f32_e32 v228, v228
	v_exp_f32_e32 v229, v229
	v_mfma_f32_32x32x16_bf16 v[64:79], v[112:115], v[136:139], v[64:79]
	v_add_f32_e32 v164, v222, v164
	v_add_f32_e32 v165, v223, v165
	v_add_f32_e32 v164, v224, v164
	v_add_f32_e32 v165, v225, v165
	v_cvt_pk_bf16_f32 v222, v222, v223
	v_cvt_pk_bf16_f32 v223, v224, v225
	v_add_f32_e32 v164, v226, v164
	v_add_f32_e32 v165, v227, v165
	v_add_f32_e32 v164, v228, v164
	v_add_f32_e32 v165, v229, v165
	v_cvt_pk_bf16_f32 v224, v226, v227
	v_cvt_pk_bf16_f32 v225, v228, v229
	v_cndmask_b32_e64 v222, v222, 0, s[72:73]
	v_cndmask_b32_e64 v223, v223, 0, s[72:73]
	v_cndmask_b32_e64 v224, v224, 0, s[72:73]
	v_cndmask_b32_e64 v225, v225, 0, s[72:73]
	v_exp_f32_e32 v230, v230
	v_exp_f32_e32 v231, v231
	s_waitcnt lgkmcnt(4)
	v_mfma_f32_32x32x16_bf16 v[48:63], v[144:147], v[222:225], v[48:63]
	ds_read_b128 v[144:147], v187 offset:13920
	v_exp_f32_e32 v232, v232
	v_exp_f32_e32 v233, v233
	s_waitcnt lgkmcnt(2)
	v_mfma_f32_32x32x16_bf16 v[32:47], v[148:151], v[222:225], v[32:47]
	v_exp_f32_e32 v234, v234
	v_exp_f32_e32 v235, v235
	v_mfma_f32_32x32x16_bf16 v[80:95], v[116:119], v[140:143], v[80:95]
	v_exp_f32_e32 v236, v236
	v_exp_f32_e32 v237, v237
	v_mfma_f32_32x32x16_bf16 v[64:79], v[120:123], v[140:143], v[64:79]
	v_add_f32_e32 v164, v230, v164
	v_add_f32_e32 v165, v231, v165
	v_add_f32_e32 v164, v232, v164
	v_add_f32_e32 v165, v233, v165
	v_cvt_pk_bf16_f32 v230, v230, v231
	v_cvt_pk_bf16_f32 v231, v232, v233
	v_add_f32_e32 v164, v234, v164
	v_add_f32_e32 v165, v235, v165
	v_add_f32_e32 v164, v236, v164
	v_add_f32_e32 v165, v237, v165
	v_cvt_pk_bf16_f32 v232, v234, v235
	v_cvt_pk_bf16_f32 v233, v236, v237
	v_cndmask_b32_e64 v230, v230, 0, s[72:73]
	v_cndmask_b32_e64 v231, v231, 0, s[72:73]
	v_cndmask_b32_e64 v232, v232, 0, s[72:73]
	v_cndmask_b32_e64 v233, v233, 0, s[72:73]
	s_nop 1
	s_waitcnt lgkmcnt(1)
	v_mfma_f32_32x32x16_bf16 v[48:63], v[124:127], v[230:233], v[48:63]
	s_waitcnt lgkmcnt(0)
	v_mfma_f32_32x32x16_bf16 v[32:47], v[144:147], v[230:233], v[32:47]
	v_add_f32_e32 v164, v164, v165
	v_cndmask_b32_e64 v164, v164, 0, s[72:73]
	v_add_f32_e32 v106, v106, v164
	v_cmp_lt_f32_e32 vcc, 0x4b800000, v164
	s_cbranch_vccz .Lsel_noresc_1b
	s_nop 15
	s_nop 15
	v_mov_b32_e32 v107, v164
	s_nop 1
	v_permlane32_swap_b32_e32 v164, v107
	v_add_f32_e32 v164, v164, v107
	v_log_f32_e32 v160, v164
	s_nop 0
	v_max_f32_e32 v160, 0, v160
	v_exp_f32_e64 v162, -v160
	v_sub_f32_e32 v2, v2, v160
	v_sub_f32_e32 v3, v3, v160
	v_sub_f32_e32 v4, v4, v160
	v_sub_f32_e32 v5, v5, v160
	v_sub_f32_e32 v6, v6, v160
	v_sub_f32_e32 v7, v7, v160
	v_sub_f32_e32 v8, v8, v160
	v_sub_f32_e32 v9, v9, v160
	v_sub_f32_e32 v10, v10, v160
	v_sub_f32_e32 v11, v11, v160
	v_sub_f32_e32 v12, v12, v160
	v_sub_f32_e32 v13, v13, v160
	v_sub_f32_e32 v14, v14, v160
	v_sub_f32_e32 v15, v15, v160
	v_sub_f32_e32 v16, v16, v160
	v_sub_f32_e32 v17, v17, v160
	v_mul_f32_e32 v106, v106, v162
	v_pk_mul_f32 v[48:49], v[48:49], v[162:163] op_sel_hi:[1,0]
	v_pk_mul_f32 v[32:33], v[32:33], v[162:163] op_sel_hi:[1,0]
	v_pk_mul_f32 v[50:51], v[50:51], v[162:163] op_sel_hi:[1,0]
	v_pk_mul_f32 v[34:35], v[34:35], v[162:163] op_sel_hi:[1,0]
	v_pk_mul_f32 v[52:53], v[52:53], v[162:163] op_sel_hi:[1,0]
	v_pk_mul_f32 v[36:37], v[36:37], v[162:163] op_sel_hi:[1,0]
	v_pk_mul_f32 v[54:55], v[54:55], v[162:163] op_sel_hi:[1,0]
	v_pk_mul_f32 v[38:39], v[38:39], v[162:163] op_sel_hi:[1,0]
	v_pk_mul_f32 v[56:57], v[56:57], v[162:163] op_sel_hi:[1,0]
	v_pk_mul_f32 v[40:41], v[40:41], v[162:163] op_sel_hi:[1,0]
	v_pk_mul_f32 v[58:59], v[58:59], v[162:163] op_sel_hi:[1,0]
	v_pk_mul_f32 v[42:43], v[42:43], v[162:163] op_sel_hi:[1,0]
	v_pk_mul_f32 v[60:61], v[60:61], v[162:163] op_sel_hi:[1,0]
	v_pk_mul_f32 v[44:45], v[44:45], v[162:163] op_sel_hi:[1,0]
	v_pk_mul_f32 v[62:63], v[62:63], v[162:163] op_sel_hi:[1,0]
	v_pk_mul_f32 v[46:47], v[46:47], v[162:163] op_sel_hi:[1,0]
	v_pk_add_f32 v[80:81], v[80:81], v[160:161] op_sel_hi:[1,0] neg_lo:[0,1] neg_hi:[0,1]
	v_pk_add_f32 v[64:65], v[64:65], v[160:161] op_sel_hi:[1,0] neg_lo:[0,1] neg_hi:[0,1]
	v_pk_add_f32 v[82:83], v[82:83], v[160:161] op_sel_hi:[1,0] neg_lo:[0,1] neg_hi:[0,1]
	v_pk_add_f32 v[66:67], v[66:67], v[160:161] op_sel_hi:[1,0] neg_lo:[0,1] neg_hi:[0,1]
	v_pk_add_f32 v[84:85], v[84:85], v[160:161] op_sel_hi:[1,0] neg_lo:[0,1] neg_hi:[0,1]
	v_pk_add_f32 v[68:69], v[68:69], v[160:161] op_sel_hi:[1,0] neg_lo:[0,1] neg_hi:[0,1]
	v_pk_add_f32 v[86:87], v[86:87], v[160:161] op_sel_hi:[1,0] neg_lo:[0,1] neg_hi:[0,1]
	v_pk_add_f32 v[70:71], v[70:71], v[160:161] op_sel_hi:[1,0] neg_lo:[0,1] neg_hi:[0,1]
	v_pk_add_f32 v[88:89], v[88:89], v[160:161] op_sel_hi:[1,0] neg_lo:[0,1] neg_hi:[0,1]
	v_pk_add_f32 v[72:73], v[72:73], v[160:161] op_sel_hi:[1,0] neg_lo:[0,1] neg_hi:[0,1]
	v_pk_add_f32 v[90:91], v[90:91], v[160:161] op_sel_hi:[1,0] neg_lo:[0,1] neg_hi:[0,1]
	v_pk_add_f32 v[74:75], v[74:75], v[160:161] op_sel_hi:[1,0] neg_lo:[0,1] neg_hi:[0,1]
	v_pk_add_f32 v[92:93], v[92:93], v[160:161] op_sel_hi:[1,0] neg_lo:[0,1] neg_hi:[0,1]
	v_pk_add_f32 v[76:77], v[76:77], v[160:161] op_sel_hi:[1,0] neg_lo:[0,1] neg_hi:[0,1]
	v_pk_add_f32 v[94:95], v[94:95], v[160:161] op_sel_hi:[1,0] neg_lo:[0,1] neg_hi:[0,1]
	v_pk_add_f32 v[78:79], v[78:79], v[160:161] op_sel_hi:[1,0] neg_lo:[0,1] neg_hi:[0,1]
	s_nop 1

.Lsel_nodiag_1c:
	v_add_u32_e32 v187, s81, v208
	ds_read_b128 v[124:127], v187 offset:9216
	ds_read_b128 v[144:147], v187 offset:13824
	ds_read_b128 v[148:151], v187 offset:9248
	v_exp_f32_e32 v238, v238
	v_exp_f32_e32 v239, v239
	v_exp_f32_e32 v240, v240
	v_exp_f32_e32 v241, v241
	v_exp_f32_e32 v242, v242
	v_exp_f32_e32 v243, v243
	v_exp_f32_e32 v244, v244
	v_exp_f32_e32 v245, v245
	v_add_f32_e32 v164, 0, v238
	v_add_f32_e32 v165, 0, v239
	v_add_f32_e32 v164, v240, v164
	v_add_f32_e32 v165, v241, v165
	v_cvt_pk_bf16_f32 v238, v238, v239
	v_cvt_pk_bf16_f32 v239, v240, v241
	v_add_f32_e32 v164, v242, v164
	v_add_f32_e32 v165, v243, v165
	v_add_f32_e32 v164, v244, v164
	v_add_f32_e32 v165, v245, v165
	v_cvt_pk_bf16_f32 v240, v242, v243
	v_cvt_pk_bf16_f32 v241, v244, v245
	v_cndmask_b32_e64 v238, v238, 0, s[72:73]
	v_cndmask_b32_e64 v239, v239, 0, s[72:73]
	v_cndmask_b32_e64 v240, v240, 0, s[72:73]
	v_cndmask_b32_e64 v241, v241, 0, s[72:73]
	v_exp_f32_e32 v246, v246
	v_exp_f32_e32 v247, v247
	s_waitcnt lgkmcnt(2)
	v_mfma_f32_32x32x16_bf16 v[48:63], v[124:127], v[238:241], v[48:63]
	ds_read_b128 v[124:127], v187 offset:13856
	v_exp_f32_e32 v248, v248
	v_exp_f32_e32 v249, v249
	s_waitcnt lgkmcnt(2)
	v_mfma_f32_32x32x16_bf16 v[32:47], v[144:147], v[238:241], v[32:47]
	ds_read_b128 v[144:147], v187 offset:9280
	v_exp_f32_e32 v250, v250
	v_exp_f32_e32 v251, v251
	v_exp_f32_e32 v252, v252
	v_exp_f32_e32 v253, v253
	v_add_f32_e32 v164, v246, v164
	v_add_f32_e32 v165, v247, v165
	v_add_f32_e32 v164, v248, v164
	v_add_f32_e32 v165, v249, v165
	v_cvt_pk_bf16_f32 v246, v246, v247
	v_cvt_pk_bf16_f32 v247, v248, v249
	v_add_f32_e32 v164, v250, v164
	v_add_f32_e32 v165, v251, v165
	v_add_f32_e32 v164, v252, v164
	v_add_f32_e32 v165, v253, v165
	v_cvt_pk_bf16_f32 v248, v250, v251
	v_cvt_pk_bf16_f32 v249, v252, v253
	v_cndmask_b32_e64 v246, v246, 0, s[72:73]
	v_cndmask_b32_e64 v247, v247, 0, s[72:73]
	v_cndmask_b32_e64 v248, v248, 0, s[72:73]
	v_cndmask_b32_e64 v249, v249, 0, s[72:73]
	v_exp_f32_e32 v222, v222
	v_exp_f32_e32 v223, v223
	s_waitcnt lgkmcnt(2)
	v_mfma_f32_32x32x16_bf16 v[48:63], v[148:151], v[246:249], v[48:63]
	ds_read_b128 v[148:151], v187 offset:13888
	v_exp_f32_e32 v224, v224
	v_exp_f32_e32 v225, v225
	s_waitcnt lgkmcnt(2)
	v_mfma_f32_32x32x16_bf16 v[32:47], v[124:127], v[246:249], v[32:47]
	ds_read_b128 v[124:127], v187 offset:9312
	v_exp_f32_e32 v226, v226
	v_exp_f32_e32 v227, v227
	v_exp_f32_e32 v228, v228
	v_exp_f32_e32 v229, v229
	v_add_f32_e32 v164, v222, v164
	v_add_f32_e32 v165, v223, v165
	v_add_f32_e32 v164, v224, v164
	v_add_f32_e32 v165, v225, v165
	v_cvt_pk_bf16_f32 v222, v222, v223
	v_cvt_pk_bf16_f32 v223, v224, v225
	v_add_f32_e32 v164, v226, v164
	v_add_f32_e32 v165, v227, v165
	v_add_f32_e32 v164, v228, v164
	v_add_f32_e32 v165, v229, v165
	v_cvt_pk_bf16_f32 v224, v226, v227
	v_cvt_pk_bf16_f32 v225, v228, v229
	v_cndmask_b32_e64 v222, v222, 0, s[72:73]
	v_cndmask_b32_e64 v223, v223, 0, s[72:73]
	v_cndmask_b32_e64 v224, v224, 0, s[72:73]
	v_cndmask_b32_e64 v225, v225, 0, s[72:73]
	v_exp_f32_e32 v230, v230
	v_exp_f32_e32 v231, v231
	s_waitcnt lgkmcnt(2)
	v_mfma_f32_32x32x16_bf16 v[48:63], v[144:147], v[222:225], v[48:63]
	ds_read_b128 v[144:147], v187 offset:13920
	v_exp_f32_e32 v232, v232
	v_exp_f32_e32 v233, v233
	s_waitcnt lgkmcnt(2)
	v_mfma_f32_32x32x16_bf16 v[32:47], v[148:151], v[222:225], v[32:47]
	v_exp_f32_e32 v234, v234
	v_exp_f32_e32 v235, v235
	v_exp_f32_e32 v236, v236
	v_exp_f32_e32 v237, v237
	v_add_f32_e32 v164, v230, v164
	v_add_f32_e32 v165, v231, v165
	v_add_f32_e32 v164, v232, v164
	v_add_f32_e32 v165, v233, v165
	v_cvt_pk_bf16_f32 v230, v230, v231
	v_cvt_pk_bf16_f32 v231, v232, v233
	v_add_f32_e32 v164, v234, v164
	v_add_f32_e32 v165, v235, v165
	v_add_f32_e32 v164, v236, v164
	v_add_f32_e32 v165, v237, v165
	v_cvt_pk_bf16_f32 v232, v234, v235
	v_cvt_pk_bf16_f32 v233, v236, v237
	v_cndmask_b32_e64 v230, v230, 0, s[72:73]
	v_cndmask_b32_e64 v231, v231, 0, s[72:73]
	v_cndmask_b32_e64 v232, v232, 0, s[72:73]
	v_cndmask_b32_e64 v233, v233, 0, s[72:73]
	s_nop 1
	s_waitcnt lgkmcnt(1)
	v_mfma_f32_32x32x16_bf16 v[48:63], v[124:127], v[230:233], v[48:63]
	s_waitcnt lgkmcnt(0)
	v_mfma_f32_32x32x16_bf16 v[32:47], v[144:147], v[230:233], v[32:47]
	v_add_f32_e32 v164, v164, v165
	v_cndmask_b32_e64 v164, v164, 0, s[72:73]
	v_add_f32_e32 v106, v106, v164
	v_cmp_lt_f32_e32 vcc, 0x4b800000, v164
	s_cbranch_vccz .Lsel_noresc_1c
	s_nop 15
	s_nop 15
	v_mov_b32_e32 v107, v164
	s_nop 1
	v_permlane32_swap_b32_e32 v164, v107
	v_add_f32_e32 v164, v164, v107
	v_log_f32_e32 v160, v164
	s_nop 0
	v_max_f32_e32 v160, 0, v160
	v_exp_f32_e64 v162, -v160
	v_sub_f32_e32 v2, v2, v160
	v_sub_f32_e32 v3, v3, v160
	v_sub_f32_e32 v4, v4, v160
	v_sub_f32_e32 v5, v5, v160
	v_sub_f32_e32 v6, v6, v160
	v_sub_f32_e32 v7, v7, v160
	v_sub_f32_e32 v8, v8, v160
	v_sub_f32_e32 v9, v9, v160
	v_sub_f32_e32 v10, v10, v160
	v_sub_f32_e32 v11, v11, v160
	v_sub_f32_e32 v12, v12, v160
	v_sub_f32_e32 v13, v13, v160
	v_sub_f32_e32 v14, v14, v160
	v_sub_f32_e32 v15, v15, v160
	v_sub_f32_e32 v16, v16, v160
	v_sub_f32_e32 v17, v17, v160
	v_mul_f32_e32 v106, v106, v162
	v_pk_mul_f32 v[48:49], v[48:49], v[162:163] op_sel_hi:[1,0]
	v_pk_mul_f32 v[32:33], v[32:33], v[162:163] op_sel_hi:[1,0]
	v_pk_mul_f32 v[50:51], v[50:51], v[162:163] op_sel_hi:[1,0]
	v_pk_mul_f32 v[34:35], v[34:35], v[162:163] op_sel_hi:[1,0]
	v_pk_mul_f32 v[52:53], v[52:53], v[162:163] op_sel_hi:[1,0]
	v_pk_mul_f32 v[36:37], v[36:37], v[162:163] op_sel_hi:[1,0]
	v_pk_mul_f32 v[54:55], v[54:55], v[162:163] op_sel_hi:[1,0]
	v_pk_mul_f32 v[38:39], v[38:39], v[162:163] op_sel_hi:[1,0]
	v_pk_mul_f32 v[56:57], v[56:57], v[162:163] op_sel_hi:[1,0]
	v_pk_mul_f32 v[40:41], v[40:41], v[162:163] op_sel_hi:[1,0]
	v_pk_mul_f32 v[58:59], v[58:59], v[162:163] op_sel_hi:[1,0]
	v_pk_mul_f32 v[42:43], v[42:43], v[162:163] op_sel_hi:[1,0]
	v_pk_mul_f32 v[60:61], v[60:61], v[162:163] op_sel_hi:[1,0]
	v_pk_mul_f32 v[44:45], v[44:45], v[162:163] op_sel_hi:[1,0]
	v_pk_mul_f32 v[62:63], v[62:63], v[162:163] op_sel_hi:[1,0]
	v_pk_mul_f32 v[46:47], v[46:47], v[162:163] op_sel_hi:[1,0]
	s_nop 1
